# R1_0 row phase: the f32 input rows (HBM) of all four rows of a wave are loaded before the row loop instead of one row per load-wait-compute-store round
# baseline (speedup 1.0000x reference)
.LBB0_567:
	v_lshl_add_u32 v0, v107, 2, v105
	v_ashrrev_i32_e32 v0, 11, v0
	v_add_u32_e32 v0, 1, v0
	v_cmp_lt_i32_e32 vcc, s2, v107
	s_mov_b32 s10, 0
	s_nop 0
	v_cndmask_b32_e32 v0, 0, v0, vcc
	v_mul_hi_i32_i24_e32 v1, 0x6000, v0
	v_mul_i32_i24_e32 v0, 0x6000, v0
	v_lshl_add_u64 v[0:1], s[56:57], 0, v[0:1]
	v_lshl_add_u64 v[40:41], v[0:1], 0, s[6:7]
	v_lshl_add_u64 v[12:13], v[40:41], 0, v[64:65]
	v_lshl_add_u64 v[56:57], v[0:1], 0, s[14:15]
	v_lshl_add_u64 v[48:49], v[0:1], 0, s[22:23]
	global_load_dwordx4 v[0:3], v[72:73], off offset:16
	global_load_dwordx4 v[4:7], v[72:73], off
	global_load_dwordx4 v[8:11], v[12:13], off offset:16
	s_nop 0
	global_load_dwordx4 v[12:15], v[12:13], off
	s_nop 0
	global_load_dwordx4 v[16:19], v[74:75], off offset:16
	global_load_dwordx4 v[20:23], v[74:75], off
	v_lshl_add_u64 v[28:29], v[56:57], 0, v[64:65]
	v_lshl_add_u64 v[32:33], v[48:49], 0, v[64:65]
	v_lshl_add_u64 v[44:45], v[40:41], 0, v[80:81]
	v_lshl_add_u64 v[48:49], v[48:49], 0, v[80:81]
	v_lshl_add_u64 v[60:61], v[56:57], 0, v[80:81]
	global_load_dwordx4 v[24:27], v[28:29], off offset:16
	s_nop 0
	global_load_dwordx4 v[28:31], v[28:29], off
	s_nop 0
	global_load_dwordx4 v[88:91], v[32:33], off offset:16
	global_load_dwordx4 v[84:87], v[32:33], off
	s_nop 0
	global_load_dwordx4 v[32:35], v[76:77], off offset:16
	global_load_dwordx4 v[36:39], v[76:77], off
	global_load_dwordx4 v[40:43], v[44:45], off offset:16
	s_nop 0
	global_load_dwordx4 v[44:47], v[44:45], off
	s_nop 0
	global_load_dwordx4 v[96:99], v[48:49], off offset:16
	global_load_dwordx4 v[92:95], v[48:49], off
	s_nop 0
	global_load_dwordx4 v[48:51], v[78:79], off offset:16
	global_load_dwordx4 v[52:55], v[78:79], off
	global_load_dwordx4 v[56:59], v[60:61], off offset:16
	s_nop 0
	global_load_dwordx4 v[60:63], v[60:61], off
	s_waitcnt vmcnt(11)
	v_pk_add_f32 v[88:89], v[88:89], 1.0 op_sel_hi:[1,0]
	s_waitcnt vmcnt(10)
	v_pk_add_f32 v[82:83], v[86:87], 1.0 op_sel_hi:[1,0]
	v_pk_add_f32 v[84:85], v[84:85], 1.0 op_sel_hi:[1,0]
	v_pk_add_f32 v[86:87], v[90:91], 1.0 op_sel_hi:[1,0]
	s_waitcnt vmcnt(4)
	v_pk_add_f32 v[90:91], v[94:95], 1.0 op_sel_hi:[1,0]
	v_pk_add_f32 v[92:93], v[92:93], 1.0 op_sel_hi:[1,0]
	v_pk_add_f32 v[94:95], v[98:99], 1.0 op_sel_hi:[1,0]
	v_pk_add_f32 v[96:97], v[96:97], 1.0 op_sel_hi:[1,0]
	v_readfirstlane_b32 s60, v104
	s_nop 1
	s_cmp_gt_u32 s60, 0xfff
	s_cselect_b32 s62, s38, s36
	s_cselect_b32 s63, s39, s37
	s_and_b32 s60, s60, 0xfff
	s_lshl_b32 s60, s60, 12
	s_add_u32 s62, s62, s60
	s_addc_u32 s63, s63, 0
	global_load_dwordx4 v[186:189], v64, s[62:63] nt
	global_load_dwordx4 v[190:193], v64, s[62:63] offset:16 nt
	global_load_dwordx4 v[194:197], v64, s[62:63] offset:2048 nt
	global_load_dwordx4 v[198:201], v64, s[62:63] offset:2064 nt
	s_add_u32 s62, s62, 0x1000
	s_addc_u32 s63, s63, 0
	global_load_dwordx4 v[224:227], v64, s[62:63] nt
	global_load_dwordx4 v[228:231], v64, s[62:63] offset:16 nt
	global_load_dwordx4 v[232:235], v64, s[62:63] offset:2048 nt
	global_load_dwordx4 v[236:239], v64, s[62:63] offset:2064 nt
	s_add_u32 s62, s62, 0x1000
	s_addc_u32 s63, s63, 0
	global_load_dwordx4 v[240:243], v64, s[62:63] nt
	global_load_dwordx4 v[244:247], v64, s[62:63] offset:16 nt
	global_load_dwordx4 v[248:251], v64, s[62:63] offset:2048 nt
	global_load_dwordx4 v[252:255], v64, s[62:63] offset:2064 nt
	s_add_u32 s62, s62, 0x1000
	s_addc_u32 s63, s63, 0
	global_load_dwordx4 v[202:205], v64, s[62:63] nt
	global_load_dwordx4 v[206:209], v64, s[62:63] offset:16 nt
	global_load_dwordx4 v[210:213], v64, s[62:63] offset:2048 nt
	global_load_dwordx4 v[150:153], v64, s[62:63] offset:2064 nt
	s_branch .LBB0_569
.LBB0_568:
	s_or_b64 exec, exec, s[40:41]
	v_lshlrev_b64 v[98:99], 11, v[102:103]
	v_lshl_add_u64 v[102:103], v[66:67], 0, v[98:99]
	global_load_dwordx4 v[108:111], v[102:103], off
	global_load_dwordx4 v[112:115], v[102:103], off offset:1024
	v_lshl_add_u64 v[124:125], v[100:101], 0, v[64:65]
	s_cmp_eq_u32 s10, 0
	s_cbranch_scc0 .Lr1pfB_b
	s_waitcnt vmcnt(16)
	v_mov_b32_e32 v100, v228
	v_mov_b32_e32 v101, v229
	v_mov_b32_e32 v102, v230
	v_mov_b32_e32 v103, v231
	v_mov_b32_e32 v116, v224
	v_mov_b32_e32 v117, v225
	v_mov_b32_e32 v118, v226
	v_mov_b32_e32 v119, v227
	v_mov_b32_e32 v120, v236
	v_mov_b32_e32 v121, v237
	v_mov_b32_e32 v122, v238
	v_mov_b32_e32 v123, v239
	v_mov_b32_e32 v124, v232
	v_mov_b32_e32 v125, v233
	v_mov_b32_e32 v126, v234
	v_mov_b32_e32 v127, v235
	s_branch .Lr1pfB_d
.Lr1pfB_b:
	s_waitcnt vmcnt(20)
	v_mov_b32_e32 v100, v206
	v_mov_b32_e32 v101, v207
	v_mov_b32_e32 v102, v208
	v_mov_b32_e32 v103, v209
	v_mov_b32_e32 v116, v202
	v_mov_b32_e32 v117, v203
	v_mov_b32_e32 v118, v204
	v_mov_b32_e32 v119, v205
	v_mov_b32_e32 v120, v150
	v_mov_b32_e32 v121, v151
	v_mov_b32_e32 v122, v152
	v_mov_b32_e32 v123, v153
	v_mov_b32_e32 v124, v210
	v_mov_b32_e32 v125, v211
	v_mov_b32_e32 v126, v212
	v_mov_b32_e32 v127, v213
.Lr1pfB_d:
	s_nop 0
	s_add_i32 s10, s10, 2
	s_cmp_eq_u32 s10, 4
	s_waitcnt vmcnt(1)
	v_and_b32_e32 v131, 0xffff0000, v110
	v_and_b32_e32 v130, 0xffff0000, v108
	v_lshlrev_b32_e32 v129, 16, v110
	v_lshlrev_b32_e32 v128, 16, v108
	v_lshlrev_b32_e32 v132, 16, v109
	v_and_b32_e32 v110, 0xffff0000, v109
	s_waitcnt vmcnt(0)
	v_lshlrev_b32_e32 v109, 16, v112
	v_lshlrev_b32_e32 v108, 16, v114
	v_and_b32_e32 v135, 0xffff0000, v112
	v_and_b32_e32 v134, 0xffff0000, v114
	v_lshlrev_b32_e32 v136, 16, v115
	v_and_b32_e32 v112, 0xffff0000, v115
	v_pk_mul_f32 v[114:115], v[130:131], v[130:131]
	v_lshlrev_b32_e32 v133, 16, v111
	v_pk_mul_f32 v[138:139], v[134:135], v[134:135]
	v_pk_fma_f32 v[114:115], v[128:129], v[128:129], v[114:115]
	v_and_b32_e32 v111, 0xffff0000, v111
	v_lshlrev_b32_e32 v137, 16, v113
	v_pk_fma_f32 v[138:139], v[108:109], v[108:109], v[138:139]
	v_pk_fma_f32 v[114:115], v[132:133], v[132:133], v[114:115]
	v_and_b32_e32 v113, 0xffff0000, v113
	v_pk_fma_f32 v[138:139], v[136:137], v[136:137], v[138:139]
	v_pk_fma_f32 v[114:115], v[110:111], v[110:111], v[114:115]
	v_pk_fma_f32 v[138:139], v[112:113], v[112:113], v[138:139]
	v_add_f32_e32 v114, v114, v115
	v_add_f32_e32 v114, v114, v139
	v_add_f32_e32 v114, v138, v114
	v_mov_b32_e32 v115, v114
	v_mov_b32_e32 v160, v114
	s_nop 1
	v_permlane32_swap_b32_e32 v115, v160
	v_mov_b32_e32 v139, v130
	v_mov_b32_e32 v130, v129
	v_mov_b32_e32 v129, v113
	v_mov_b32_e32 v141, v135
	s_waitcnt lgkmcnt(0)
	v_add_f32_e32 v114, v115, v160
	v_mov_b32_e32 v115, v114
	v_mov_b32_e32 v160, v114
	s_nop 1
	v_permlane16_swap_b32_e32 v115, v160
	s_waitcnt lgkmcnt(0)
	v_add_f32_e32 v114, v115, v160
	s_nop 1
	v_mov_b32_dpp v115, v114 row_ror:8 row_mask:0xf bank_mask:0xf
	s_waitcnt lgkmcnt(0)
	v_add_f32_e32 v115, v114, v115
	s_nop 1
	v_mov_b32_dpp v138, v115 row_ror:4 row_mask:0xf bank_mask:0xf
	v_mov_b32_e32 v114, v132
	s_waitcnt lgkmcnt(0)
	v_add_f32_e32 v132, v115, v138
	s_nop 1
	v_mov_b32_dpp v140, v132 row_ror:2 row_mask:0xf bank_mask:0xf
	v_mov_b32_e32 v115, v110
	v_mov_b32_e32 v138, v128
	v_mov_b32_e32 v128, v137
	v_mov_b32_e32 v137, v112
	s_waitcnt lgkmcnt(0)
	v_add_f32_e32 v110, v132, v140
	s_nop 1
	v_mov_b32_dpp v132, v110 row_ror:1 row_mask:0xf bank_mask:0xf
	v_mov_b32_e32 v140, v109
	s_waitcnt lgkmcnt(0)
	v_add_f32_e32 v109, v110, v132
	v_fmamk_f32 v109, v109, 0x3a800000, v106
	v_mul_f32_e32 v110, 0x4b800000, v109
	v_cmp_gt_f32_e32 vcc, s8, v109
	s_nop 1
	v_cndmask_b32_e32 v109, v109, v110, vcc
	v_rsq_f32_e32 v113, v109
	v_mov_b32_e32 v109, v134
	v_mov_b32_e32 v110, v133
	v_mul_f32_e32 v112, 0x45800000, v113
	v_cndmask_b32_e32 v112, v113, v112, vcc
	v_pk_mul_f32 v[132:133], v[112:113], v[138:139] op_sel_hi:[0,1]
	v_pk_mul_f32 v[130:131], v[112:113], v[130:131] op_sel_hi:[0,1]
	v_pk_mul_f32 v[114:115], v[112:113], v[114:115] op_sel_hi:[0,1]
	v_pk_mul_f32 v[110:111], v[112:113], v[110:111] op_sel_hi:[0,1]
	v_pk_mul_f32 v[128:129], v[112:113], v[128:129] op_sel_hi:[0,1]
	v_pk_mul_f32 v[134:135], v[112:113], v[140:141] op_sel_hi:[0,1]
	v_pk_mul_f32 v[136:137], v[112:113], v[136:137] op_sel_hi:[0,1]
	v_pk_mul_f32 v[108:109], v[112:113], v[108:109] op_sel_hi:[0,1]
	v_pk_mul_f32 v[112:113], v[4:5], v[132:133]
	v_pk_mul_f32 v[130:131], v[0:1], v[130:131]
	v_pk_mul_f32 v[132:133], v[36:37], v[134:135]
	v_pk_mul_f32 v[108:109], v[32:33], v[108:109]
	s_nop 0
	v_pk_fma_f32 v[112:113], v[12:13], v[112:113], v[116:117]
	v_pk_fma_f32 v[116:117], v[8:9], v[130:131], v[100:101]
	v_pk_mul_f32 v[114:115], v[6:7], v[114:115]
	v_pk_mul_f32 v[110:111], v[2:3], v[110:111]
	s_nop 0
	v_pk_fma_f32 v[124:125], v[44:45], v[132:133], v[124:125]
	v_pk_fma_f32 v[120:121], v[40:41], v[108:109], v[120:121]
	v_mov_b32_e32 v108, v113
	v_mov_b32_e32 v109, v117
	v_pk_mul_f32 v[128:129], v[38:39], v[128:129]
	v_pk_mul_f32 v[134:135], v[34:35], v[136:137]
	v_pk_fma_f32 v[114:115], v[14:15], v[114:115], v[118:119]
	v_pk_fma_f32 v[102:103], v[10:11], v[110:111], v[102:103]
	v_mov_b32_e32 v100, v112
	v_mov_b32_e32 v101, v116
	v_mov_b32_e32 v130, v121
	v_mov_b32_e32 v131, v125
	v_pk_mul_f32 v[108:109], v[108:109], v[108:109]
	v_pk_fma_f32 v[118:119], v[46:47], v[128:129], v[126:127]
	v_pk_fma_f32 v[122:123], v[42:43], v[134:135], v[122:123]
	v_mov_b32_e32 v110, v114
	v_mov_b32_e32 v111, v102
	v_mov_b32_e32 v128, v120
	v_mov_b32_e32 v129, v124
	v_pk_mul_f32 v[130:131], v[130:131], v[130:131]
	v_pk_fma_f32 v[100:101], v[100:101], v[100:101], v[108:109]
	v_mov_b32_e32 v126, v115
	v_mov_b32_e32 v127, v103
	v_mov_b32_e32 v132, v122
	v_mov_b32_e32 v133, v118
	v_pk_fma_f32 v[108:109], v[128:129], v[128:129], v[130:131]
	v_pk_fma_f32 v[100:101], v[110:111], v[110:111], v[100:101]
	v_mov_b32_e32 v134, v123
	v_mov_b32_e32 v135, v119
	v_pk_fma_f32 v[108:109], v[132:133], v[132:133], v[108:109]
	v_pk_fma_f32 v[100:101], v[126:127], v[126:127], v[100:101]
	v_pk_fma_f32 v[108:109], v[134:135], v[134:135], v[108:109]
	v_add_f32_e32 v100, v100, v101
	v_add_f32_e32 v100, v109, v100
	v_add_f32_e32 v100, v108, v100
	v_mov_b32_e32 v101, v100
	v_mov_b32_e32 v160, v100
	s_nop 1
	v_permlane32_swap_b32_e32 v101, v160
	v_lshl_add_u64 v[126:127], v[68:69], 0, v[98:99]
	v_lshl_add_u64 v[128:129], v[70:71], 0, v[98:99]
	v_cvt_pk_bf16_f32 v98, v112, v113
	v_cvt_pk_bf16_f32 v99, v114, v115
	s_waitcnt lgkmcnt(0)
	v_add_f32_e32 v100, v101, v160
	v_mov_b32_e32 v101, v100
	v_mov_b32_e32 v160, v100
	s_nop 1
	v_permlane16_swap_b32_e32 v101, v160
	v_cvt_pk_bf16_f32 v109, v118, v119
	v_cvt_pk_bf16_f32 v110, v120, v121
	s_waitcnt lgkmcnt(0)
	v_add_f32_e32 v100, v101, v160
	s_nop 1
	v_mov_b32_dpp v101, v100 row_ror:8 row_mask:0xf bank_mask:0xf
	s_waitcnt lgkmcnt(0)
	v_add_f32_e32 v100, v100, v101
	s_nop 1
	v_mov_b32_dpp v101, v100 row_ror:4 row_mask:0xf bank_mask:0xf
	s_waitcnt lgkmcnt(0)
	v_add_f32_e32 v101, v100, v101
	s_nop 1
	v_mov_b32_dpp v108, v101 row_ror:2 row_mask:0xf bank_mask:0xf
	v_cvt_pk_bf16_f32 v100, v116, v117
	s_waitcnt lgkmcnt(0)
	v_add_f32_e32 v111, v101, v108
	s_nop 1
	v_mov_b32_dpp v130, v111 row_ror:1 row_mask:0xf bank_mask:0xf
	v_cvt_pk_bf16_f32 v101, v102, v103
	v_cvt_pk_bf16_f32 v108, v124, v125
	s_waitcnt lgkmcnt(0)
	v_add_f32_e32 v111, v111, v130
	v_fmamk_f32 v111, v111, 0x3a800000, v106
	v_mul_f32_e32 v130, 0x4b800000, v111
	v_cmp_gt_f32_e32 vcc, s8, v111
	s_nop 1
	v_cndmask_b32_e32 v111, v111, v130, vcc
	v_rsq_f32_e32 v130, v111
	v_cvt_pk_bf16_f32 v111, v122, v123
	global_store_dwordx4 v[126:127], v[98:101], off sc1
	global_store_dwordx4 v[126:127], v[108:111], off offset:1024 sc1
	s_nop 0
	v_mul_f32_e32 v98, 0x45800000, v130
	v_cndmask_b32_e32 v98, v130, v98, vcc
	v_pk_mul_f32 v[100:101], v[114:115], v[98:99] op_sel_hi:[1,0]
	v_pk_mul_f32 v[108:109], v[112:113], v[98:99] op_sel_hi:[1,0]
	v_pk_mul_f32 v[102:103], v[102:103], v[98:99] op_sel_hi:[1,0]
	v_pk_mul_f32 v[110:111], v[116:117], v[98:99] op_sel_hi:[1,0]
	v_pk_mul_f32 v[112:113], v[118:119], v[98:99] op_sel_hi:[1,0]
	v_pk_mul_f32 v[114:115], v[124:125], v[98:99] op_sel_hi:[1,0]
	v_pk_mul_f32 v[116:117], v[122:123], v[98:99] op_sel_hi:[1,0]
	v_pk_mul_f32 v[98:99], v[120:121], v[98:99] op_sel_hi:[1,0]
	v_pk_mul_f32 v[108:109], v[20:21], v[108:109]
	v_pk_mul_f32 v[100:101], v[22:23], v[100:101]
	v_pk_mul_f32 v[110:111], v[16:17], v[110:111]
	v_pk_mul_f32 v[102:103], v[18:19], v[102:103]
	v_pk_mul_f32 v[114:115], v[52:53], v[114:115]
	v_pk_mul_f32 v[112:113], v[54:55], v[112:113]
	v_pk_mul_f32 v[98:99], v[48:49], v[98:99]
	v_pk_mul_f32 v[116:117], v[50:51], v[116:117]
	v_pk_fma_f32 v[100:101], v[82:83], v[100:101], v[30:31]
	v_pk_fma_f32 v[108:109], v[84:85], v[108:109], v[28:29]
	v_pk_fma_f32 v[102:103], v[86:87], v[102:103], v[26:27]
	v_pk_fma_f32 v[110:111], v[88:89], v[110:111], v[24:25]
	v_pk_fma_f32 v[112:113], v[90:91], v[112:113], v[62:63]
	v_pk_fma_f32 v[114:115], v[92:93], v[114:115], v[60:61]
	v_pk_fma_f32 v[116:117], v[94:95], v[116:117], v[58:59]
	v_pk_fma_f32 v[118:119], v[96:97], v[98:99], v[56:57]
	v_cvt_pk_bf16_f32 v98, v108, v109
	v_cvt_pk_bf16_f32 v99, v100, v101
	v_cvt_pk_bf16_f32 v100, v110, v111
	v_cvt_pk_bf16_f32 v101, v102, v103
	v_cvt_pk_bf16_f32 v108, v114, v115
	v_cvt_pk_bf16_f32 v109, v112, v113
	v_cvt_pk_bf16_f32 v110, v118, v119
	v_cvt_pk_bf16_f32 v111, v116, v117
	global_store_dwordx4 v[128:129], v[98:101], off sc1
	global_store_dwordx4 v[128:129], v[108:111], off offset:1024 sc1
	s_cbranch_scc1 .LBB0_566
.LBB0_569:
	v_add_u32_e32 v98, s10, v104
	v_cmp_lt_i32_e32 vcc, s3, v98
	s_and_saveexec_b64 s[16:17], vcc
	s_xor_b64 s[40:41], exec, s[16:17]
	v_add_u32_e32 v100, 0xfffff000, v98
	v_mov_b32_e32 v101, v65
	v_lshlrev_b64 v[100:101], 12, v[100:101]
	v_lshl_add_u64 v[102:103], s[38:39], 0, v[100:101]
	v_mov_b32_e32 v99, v65
	s_andn2_saveexec_b64 s[40:41], s[40:41]
	v_ashrrev_i32_e32 v99, 31, v98
	v_lshlrev_b64 v[100:101], 12, v[98:99]
	v_lshl_add_u64 v[102:103], s[36:37], 0, v[100:101]
	s_or_b64 exec, exec, s[40:41]
	v_lshlrev_b64 v[100:101], 11, v[98:99]
	v_lshl_add_u64 v[112:113], v[66:67], 0, v[100:101]
	global_load_dwordx4 v[108:111], v[112:113], off
	s_nop 0
	global_load_dwordx4 v[112:115], v[112:113], off offset:1024
	v_lshl_add_u64 v[102:103], v[102:103], 0, v[64:65]
	s_cmp_eq_u32 s10, 0
	s_cbranch_scc0 .Lr1pfA_b
	s_waitcnt vmcnt(14)
	v_mov_b32_e32 v116, v190
	v_mov_b32_e32 v117, v191
	v_mov_b32_e32 v118, v192
	v_mov_b32_e32 v119, v193
	v_mov_b32_e32 v120, v186
	v_mov_b32_e32 v121, v187
	v_mov_b32_e32 v122, v188
	v_mov_b32_e32 v123, v189
	v_mov_b32_e32 v124, v198
	v_mov_b32_e32 v125, v199
	v_mov_b32_e32 v126, v200
	v_mov_b32_e32 v127, v201
	v_mov_b32_e32 v128, v194
	v_mov_b32_e32 v129, v195
	v_mov_b32_e32 v130, v196
	v_mov_b32_e32 v131, v197
	s_branch .Lr1pfA_d
.Lr1pfA_b:
	s_waitcnt vmcnt(18)
	v_mov_b32_e32 v116, v244
	v_mov_b32_e32 v117, v245
	v_mov_b32_e32 v118, v246
	v_mov_b32_e32 v119, v247
	v_mov_b32_e32 v120, v240
	v_mov_b32_e32 v121, v241
	v_mov_b32_e32 v122, v242
	v_mov_b32_e32 v123, v243
	v_mov_b32_e32 v124, v252
	v_mov_b32_e32 v125, v253
	v_mov_b32_e32 v126, v254
	v_mov_b32_e32 v127, v255
	v_mov_b32_e32 v128, v248
	v_mov_b32_e32 v129, v249
	v_mov_b32_e32 v130, v250
	v_mov_b32_e32 v131, v251
.Lr1pfA_d:
	s_waitcnt vmcnt(1)
	v_and_b32_e32 v133, 0xffff0000, v110
	v_and_b32_e32 v132, 0xffff0000, v108
	v_lshlrev_b32_e32 v103, 16, v110
	v_lshlrev_b32_e32 v102, 16, v108
	v_lshlrev_b32_e32 v134, 16, v109
	v_and_b32_e32 v110, 0xffff0000, v109
	s_waitcnt vmcnt(0)
	v_lshlrev_b32_e32 v109, 16, v112
	v_lshlrev_b32_e32 v108, 16, v114
	v_and_b32_e32 v137, 0xffff0000, v112
	v_and_b32_e32 v136, 0xffff0000, v114
	v_lshlrev_b32_e32 v138, 16, v115
	v_and_b32_e32 v112, 0xffff0000, v115
	v_pk_mul_f32 v[114:115], v[132:133], v[132:133]
	v_lshlrev_b32_e32 v135, 16, v111
	v_pk_mul_f32 v[140:141], v[136:137], v[136:137]
	v_pk_fma_f32 v[114:115], v[102:103], v[102:103], v[114:115]
	v_and_b32_e32 v111, 0xffff0000, v111
	v_lshlrev_b32_e32 v139, 16, v113
	v_pk_fma_f32 v[140:141], v[108:109], v[108:109], v[140:141]
	v_pk_fma_f32 v[114:115], v[134:135], v[134:135], v[114:115]
	v_and_b32_e32 v113, 0xffff0000, v113
	v_pk_fma_f32 v[140:141], v[138:139], v[138:139], v[140:141]
	v_pk_fma_f32 v[114:115], v[110:111], v[110:111], v[114:115]
	v_pk_fma_f32 v[140:141], v[112:113], v[112:113], v[140:141]
	v_add_f32_e32 v99, v114, v115
	v_add_f32_e32 v99, v99, v141
	v_add_f32_e32 v99, v140, v99
	v_mov_b32_e32 v114, v99
	v_mov_b32_e32 v160, v99
	s_nop 1
	v_permlane32_swap_b32_e32 v114, v160
	v_mov_b32_e32 v142, v109
	v_mov_b32_e32 v140, v102
	v_mov_b32_e32 v102, v139
	v_mov_b32_e32 v139, v112
	s_waitcnt lgkmcnt(0)
	v_add_f32_e32 v99, v114, v160
	v_mov_b32_e32 v114, v99
	v_mov_b32_e32 v160, v99
	s_nop 1
	v_permlane16_swap_b32_e32 v114, v160
	v_mov_b32_e32 v141, v132
	v_mov_b32_e32 v132, v103
	v_mov_b32_e32 v103, v113
	v_mov_b32_e32 v143, v137
	s_waitcnt lgkmcnt(0)
	v_add_f32_e32 v99, v114, v160
	s_nop 1
	v_mov_b32_dpp v114, v99 row_ror:8 row_mask:0xf bank_mask:0xf
	s_waitcnt lgkmcnt(0)
	v_add_f32_e32 v99, v99, v114
	s_nop 1
	v_mov_b32_dpp v115, v99 row_ror:4 row_mask:0xf bank_mask:0xf
	v_mov_b32_e32 v114, v134
	s_waitcnt lgkmcnt(0)
	v_add_f32_e32 v99, v99, v115
	s_nop 1
	v_mov_b32_dpp v134, v99 row_ror:2 row_mask:0xf bank_mask:0xf
	v_mov_b32_e32 v115, v110
	s_waitcnt lgkmcnt(0)
	v_add_f32_e32 v99, v99, v134
	s_nop 1
	v_mov_b32_dpp v110, v99 row_ror:1 row_mask:0xf bank_mask:0xf
	s_waitcnt lgkmcnt(0)
	v_add_f32_e32 v99, v99, v110
	v_fmamk_f32 v99, v99, 0x3a800000, v106
	v_mul_f32_e32 v109, 0x4b800000, v99
	v_cmp_gt_f32_e32 vcc, s8, v99
	v_mov_b32_e32 v110, v135
	s_nop 0
	v_cndmask_b32_e32 v99, v99, v109, vcc
	v_rsq_f32_e32 v99, v99
	v_mov_b32_e32 v109, v136
	v_mul_f32_e32 v112, 0x45800000, v99
	v_cndmask_b32_e32 v112, v99, v112, vcc
	v_pk_mul_f32 v[134:135], v[112:113], v[140:141] op_sel_hi:[0,1]
	v_pk_mul_f32 v[132:133], v[112:113], v[132:133] op_sel_hi:[0,1]
	v_pk_mul_f32 v[114:115], v[112:113], v[114:115] op_sel_hi:[0,1]
	v_pk_mul_f32 v[110:111], v[112:113], v[110:111] op_sel_hi:[0,1]
	v_pk_mul_f32 v[102:103], v[112:113], v[102:103] op_sel_hi:[0,1]
	v_pk_mul_f32 v[136:137], v[112:113], v[142:143] op_sel_hi:[0,1]
	v_pk_mul_f32 v[138:139], v[112:113], v[138:139] op_sel_hi:[0,1]
	v_pk_mul_f32 v[108:109], v[112:113], v[108:109] op_sel_hi:[0,1]
	v_pk_mul_f32 v[112:113], v[4:5], v[134:135]
	v_pk_mul_f32 v[132:133], v[0:1], v[132:133]
	v_pk_mul_f32 v[134:135], v[36:37], v[136:137]
	v_pk_mul_f32 v[108:109], v[32:33], v[108:109]
	s_nop 0
	v_pk_fma_f32 v[120:121], v[12:13], v[112:113], v[120:121]
	v_pk_fma_f32 v[116:117], v[8:9], v[132:133], v[116:117]
	v_pk_mul_f32 v[114:115], v[6:7], v[114:115]
	v_pk_mul_f32 v[110:111], v[2:3], v[110:111]
	v_pk_mul_f32 v[102:103], v[38:39], v[102:103]
	s_nop 0
	v_pk_fma_f32 v[128:129], v[44:45], v[134:135], v[128:129]
	v_pk_fma_f32 v[124:125], v[40:41], v[108:109], v[124:125]
	v_mov_b32_e32 v108, v121
	v_mov_b32_e32 v109, v117
	v_pk_mul_f32 v[136:137], v[34:35], v[138:139]
	v_pk_fma_f32 v[122:123], v[14:15], v[114:115], v[122:123]
	v_pk_fma_f32 v[118:119], v[10:11], v[110:111], v[118:119]
	v_pk_fma_f32 v[130:131], v[46:47], v[102:103], v[130:131]
	v_mov_b32_e32 v102, v120
	v_mov_b32_e32 v103, v116
	v_mov_b32_e32 v132, v125
	v_mov_b32_e32 v133, v129
	v_pk_mul_f32 v[108:109], v[108:109], v[108:109]
	v_pk_fma_f32 v[126:127], v[42:43], v[136:137], v[126:127]
	v_mov_b32_e32 v110, v122
	v_mov_b32_e32 v111, v118
	v_mov_b32_e32 v114, v124
	v_mov_b32_e32 v115, v128
	v_pk_mul_f32 v[132:133], v[132:133], v[132:133]
	v_pk_fma_f32 v[102:103], v[102:103], v[102:103], v[108:109]
	v_mov_b32_e32 v112, v123
	v_mov_b32_e32 v113, v119
	v_mov_b32_e32 v134, v126
	v_mov_b32_e32 v135, v130
	v_pk_fma_f32 v[108:109], v[114:115], v[114:115], v[132:133]
	v_pk_fma_f32 v[102:103], v[110:111], v[110:111], v[102:103]
	v_mov_b32_e32 v136, v127
	v_mov_b32_e32 v137, v131
	v_pk_fma_f32 v[108:109], v[134:135], v[134:135], v[108:109]
	v_pk_fma_f32 v[102:103], v[112:113], v[112:113], v[102:103]
	v_pk_fma_f32 v[108:109], v[136:137], v[136:137], v[108:109]
	v_add_f32_e32 v99, v102, v103
	v_add_f32_e32 v99, v109, v99
	v_add_f32_e32 v99, v108, v99
	v_mov_b32_e32 v102, v99
	v_mov_b32_e32 v160, v99
	s_nop 1
	v_permlane32_swap_b32_e32 v102, v160
	v_lshl_add_u64 v[132:133], v[68:69], 0, v[100:101]
	v_cvt_pk_bf16_f32 v108, v120, v121
	v_cvt_pk_bf16_f32 v109, v122, v123
	v_cvt_pk_bf16_f32 v110, v116, v117
	s_waitcnt lgkmcnt(0)
	v_add_f32_e32 v99, v102, v160
	v_mov_b32_e32 v102, v99
	v_mov_b32_e32 v160, v99
	s_nop 1
	v_permlane16_swap_b32_e32 v102, v160
	v_cvt_pk_bf16_f32 v111, v118, v119
	v_cvt_pk_bf16_f32 v112, v128, v129
	v_cvt_pk_bf16_f32 v113, v130, v131
	v_cvt_pk_bf16_f32 v114, v124, v125
	s_waitcnt lgkmcnt(0)
	v_add_f32_e32 v99, v102, v160
	s_nop 1
	v_mov_b32_dpp v102, v99 row_ror:8 row_mask:0xf bank_mask:0xf
	v_cvt_pk_bf16_f32 v115, v126, v127
	global_store_dwordx4 v[132:133], v[108:111], off sc1
	global_store_dwordx4 v[132:133], v[112:115], off offset:1024 sc1
	v_lshl_add_u64 v[100:101], v[70:71], 0, v[100:101]
	s_waitcnt lgkmcnt(0)
	v_add_f32_e32 v99, v99, v102
	s_nop 1
	v_mov_b32_dpp v103, v99 row_ror:4 row_mask:0xf bank_mask:0xf
	v_add_u32_e32 v102, 1, v98
	s_waitcnt lgkmcnt(0)
	v_add_f32_e32 v99, v99, v103
	s_nop 1
	v_mov_b32_dpp v103, v99 row_ror:2 row_mask:0xf bank_mask:0xf
	s_waitcnt lgkmcnt(0)
	v_add_f32_e32 v99, v99, v103
	s_nop 1
	v_mov_b32_dpp v103, v99 row_ror:1 row_mask:0xf bank_mask:0xf
	s_waitcnt lgkmcnt(0)
	v_add_f32_e32 v99, v99, v103
	v_fmamk_f32 v99, v99, 0x3a800000, v106
	v_mul_f32_e32 v103, 0x4b800000, v99
	v_cmp_gt_f32_e32 vcc, s8, v99
	s_nop 1
	v_cndmask_b32_e32 v99, v99, v103, vcc
	v_rsq_f32_e32 v99, v99
	s_nop 0
	v_mul_f32_e32 v103, 0x45800000, v99
	v_cndmask_b32_e32 v108, v99, v103, vcc
	v_pk_mul_f32 v[110:111], v[122:123], v[108:109] op_sel_hi:[1,0]
	v_pk_mul_f32 v[112:113], v[120:121], v[108:109] op_sel_hi:[1,0]
	v_pk_mul_f32 v[114:115], v[118:119], v[108:109] op_sel_hi:[1,0]
	v_pk_mul_f32 v[116:117], v[116:117], v[108:109] op_sel_hi:[1,0]
	v_pk_mul_f32 v[118:119], v[130:131], v[108:109] op_sel_hi:[1,0]
	v_pk_mul_f32 v[120:121], v[128:129], v[108:109] op_sel_hi:[1,0]
	v_pk_mul_f32 v[122:123], v[126:127], v[108:109] op_sel_hi:[1,0]
	v_pk_mul_f32 v[108:109], v[124:125], v[108:109] op_sel_hi:[1,0]
	v_pk_mul_f32 v[112:113], v[20:21], v[112:113]
	v_pk_mul_f32 v[110:111], v[22:23], v[110:111]
	v_pk_mul_f32 v[116:117], v[16:17], v[116:117]
	v_pk_mul_f32 v[114:115], v[18:19], v[114:115]
	v_pk_mul_f32 v[120:121], v[52:53], v[120:121]
	v_pk_mul_f32 v[118:119], v[54:55], v[118:119]
	v_pk_mul_f32 v[108:109], v[48:49], v[108:109]
	v_pk_mul_f32 v[122:123], v[50:51], v[122:123]
	v_pk_fma_f32 v[110:111], v[82:83], v[110:111], v[30:31]
	v_pk_fma_f32 v[112:113], v[84:85], v[112:113], v[28:29]
	v_pk_fma_f32 v[114:115], v[86:87], v[114:115], v[26:27]
	v_pk_fma_f32 v[116:117], v[88:89], v[116:117], v[24:25]
	v_pk_fma_f32 v[118:119], v[90:91], v[118:119], v[62:63]
	v_pk_fma_f32 v[120:121], v[92:93], v[120:121], v[60:61]
	v_pk_fma_f32 v[122:123], v[94:95], v[122:123], v[58:59]
	v_pk_fma_f32 v[124:125], v[96:97], v[108:109], v[56:57]
	v_cvt_pk_bf16_f32 v108, v112, v113
	v_cvt_pk_bf16_f32 v109, v110, v111
	v_cvt_pk_bf16_f32 v110, v116, v117
	v_cvt_pk_bf16_f32 v111, v114, v115
	v_cmp_lt_i32_e32 vcc, s3, v102
	v_cvt_pk_bf16_f32 v112, v120, v121
	v_cvt_pk_bf16_f32 v113, v118, v119
	v_cvt_pk_bf16_f32 v114, v124, v125
	v_cvt_pk_bf16_f32 v115, v122, v123
	global_store_dwordx4 v[100:101], v[108:111], off sc1
	global_store_dwordx4 v[100:101], v[112:115], off offset:1024 sc1
	s_and_saveexec_b64 s[16:17], vcc
	s_xor_b64 s[40:41], exec, s[16:17]
	v_add_u32_e32 v98, 0xfffff001, v98
	v_mov_b32_e32 v99, v65
	v_lshlrev_b64 v[98:99], 12, v[98:99]
	v_lshl_add_u64 v[100:101], s[38:39], 0, v[98:99]
	v_mov_b32_e32 v103, v65
	s_andn2_saveexec_b64 s[40:41], s[40:41]
	s_cbranch_execz .LBB0_568
	v_ashrrev_i32_e32 v103, 31, v102
	v_lshlrev_b64 v[98:99], 12, v[102:103]
	v_lshl_add_u64 v[100:101], s[36:37], 0, v[98:99]
	s_branch .LBB0_568
